# v27 with the conversion steps spread over every other scan loader iteration (half the instantaneous HBM traffic)
# baseline (speedup 1.0000x reference)
.LBB0_208:
	s_mov_b32 s53, 0
	s_bitcmp1_b32 s20, 5
	s_cbranch_scc1 .Lcis_a_done
	v_readlane_b32 s52, v224, 30
	s_nop 3
	s_cmp_lt_u32 s55, s52
	s_cbranch_scc0 .Lcis_a_done
	s_mov_b32 s53, 1
	s_cmp_lt_u32 s55, 0x1000
	s_cbranch_scc1 .Lcis_j_wout
	s_cmp_lt_u32 s55, 0x2000
	s_cbranch_scc1 .Lcis_j_gate
	s_cmp_lt_u32 s55, 0x6000
	s_cbranch_scc1 .Lcis_j_down
	s_cmp_lt_u32 s55, 0xa000
	s_cbranch_scc1 .Lcis_j_up
	s_cmp_lt_u32 s55, 0xb000
	s_cbranch_scc1 .Lcis_j_p
